# instruction-count trim in the VALU-bound SwiGLU epilogue: leftover s_nop pads from the removed sqrt/div chains deleted, required pads re-derived
# baseline (speedup 1.0000x reference)
.LBB0_384:
	s_waitcnt vmcnt(8)
	v_fmamk_f32 v145, v163, 0x3a800000, v154
	v_rsq_f32_e32 v145, v145
	v_lshl_or_b32 v148, s60, 7, v152
	v_ashrrev_i32_e32 v149, 31, v148
	v_lshlrev_b64 v[148:149], 1, v[148:149]
	v_mov_b32_e32 v164, v145
	v_pk_mul_f32 v[124:125], v[124:125], v[164:165] op_sel_hi:[1,0]
	v_pk_mul_f32 v[126:127], v[126:127], v[164:165] op_sel_hi:[1,0]
	v_pk_mul_f32 v[122:123], v[122:123], v[164:165] op_sel_hi:[1,0]
	v_pk_mul_f32 v[120:121], v[120:121], v[164:165] op_sel_hi:[1,0]
	v_pk_mul_f32 v[118:119], v[118:119], v[164:165] op_sel_hi:[1,0]
	v_pk_mul_f32 v[116:117], v[116:117], v[164:165] op_sel_hi:[1,0]
	v_mul_f32_e32 v145, 0xbfb8aa3b, v124
	v_mul_f32_e32 v165, 0xbfb8aa3b, v125
	v_exp_f32_e32 v145, v145
	v_exp_f32_e32 v165, v165
	v_mov_b64_e32 v[146:147], s[12:13]
	v_mad_i64_i32 v[166:167], s[8:9], v144, s59, v[146:147]
	v_pk_mul_f32 v[168:169], v[114:115], v[164:165] op_sel_hi:[1,0]
	v_add_f32_e32 v114, 1.0, v145
	v_rcp_f32_e32 v145, v114
	v_add_f32_e32 v114, 1.0, v165
	v_rcp_f32_e32 v165, v114
	v_lshl_add_u64 v[166:167], v[166:167], 0, v[148:149]
	v_pk_mul_f32 v[114:115], v[112:113], v[164:165] op_sel_hi:[1,0]
	v_mul_f32_e32 v112, v124, v145
	v_mul_f32_e32 v112, v116, v112
	v_mul_f32_e32 v116, 0xbfb8aa3b, v126
	v_mul_f32_e32 v124, 0xbfb8aa3b, v127
	v_exp_f32_e32 v116, v116
	v_exp_f32_e32 v124, v124
	v_mul_f32_e32 v113, v125, v165
	v_mul_f32_e32 v113, v117, v113
	v_add_f32_e32 v116, 1.0, v116
	v_add_f32_e32 v117, 1.0, v124
	v_rcp_f32_e32 v116, v116
	v_rcp_f32_e32 v117, v117
	v_cvt_pk_bf16_f32 v112, v112, v113
	v_mul_f32_e32 v113, v126, v116
	v_mul_f32_e32 v116, v127, v117
	v_mul_f32_e32 v117, 0xbfb8aa3b, v120
	v_mul_f32_e32 v113, v118, v113
	v_exp_f32_e32 v117, v117
	v_mul_f32_e32 v118, 0xbfb8aa3b, v121
	v_exp_f32_e32 v118, v118
	v_mul_f32_e32 v116, v119, v116
	v_cvt_pk_bf16_f32 v113, v113, v116
	v_add_f32_e32 v116, 1.0, v117
	v_rcp_f32_e32 v116, v116
	v_add_f32_e32 v117, 1.0, v118
	v_mul_f32_e32 v118, 0xbfb8aa3b, v122
	v_rcp_f32_e32 v117, v117
	v_exp_f32_e32 v118, v118
	v_mul_f32_e32 v116, v120, v116
	v_mul_f32_e32 v114, v114, v116
	v_mul_f32_e32 v116, v121, v117
	v_add_f32_e32 v117, 1.0, v118
	v_rcp_f32_e32 v117, v117
	v_mul_f32_e32 v118, 0xbfb8aa3b, v123
	v_exp_f32_e32 v118, v118
	v_mul_f32_e32 v115, v115, v116
	v_cvt_pk_bf16_f32 v114, v114, v115
	v_mul_f32_e32 v115, v122, v117
	v_fmamk_f32 v117, v162, 0x3a800000, v154
	v_rsq_f32_e32 v117, v117
	v_add_f32_e32 v116, 1.0, v118
	v_rcp_f32_e32 v116, v116
	v_mul_f32_e32 v115, v168, v115
	v_mul_f32_e32 v116, v123, v116
	v_mul_f32_e32 v116, v169, v116
	v_cvt_pk_bf16_f32 v115, v115, v116
	flat_store_dwordx4 v[166:167], v[112:115]
	s_nop 1
	v_or_b32_e32 v113, 16, v144
	v_mov_b32_e32 v112, v117
	v_pk_mul_f32 v[108:109], v[112:113], v[108:109] op_sel_hi:[0,1]
	v_mad_i64_i32 v[114:115], s[8:9], v113, s59, v[146:147]
	v_pk_mul_f32 v[110:111], v[112:113], v[110:111] op_sel_hi:[0,1]
	v_pk_mul_f32 v[106:107], v[112:113], v[106:107] op_sel_hi:[0,1]
	v_pk_mul_f32 v[104:105], v[112:113], v[104:105] op_sel_hi:[0,1]
	v_pk_mul_f32 v[102:103], v[112:113], v[102:103] op_sel_hi:[0,1]
	v_pk_mul_f32 v[100:101], v[112:113], v[100:101] op_sel_hi:[0,1]
	v_mul_f32_e32 v113, 0xbfb8aa3b, v108
	v_exp_f32_e32 v113, v113
	v_mul_f32_e32 v116, 0xbfb8aa3b, v109
	v_exp_f32_e32 v118, v116
	v_lshl_add_u64 v[114:115], v[114:115], 0, v[148:149]
	v_pk_mul_f32 v[116:117], v[112:113], v[98:99] op_sel_hi:[0,1]
	v_add_f32_e32 v98, 1.0, v113
	v_rcp_f32_e32 v113, v98
	v_add_f32_e32 v98, 1.0, v118
	v_rcp_f32_e32 v118, v98
	v_pk_mul_f32 v[98:99], v[112:113], v[96:97] op_sel_hi:[0,1]
	v_mul_f32_e32 v96, v108, v113
	v_mul_f32_e32 v96, v100, v96
	v_mul_f32_e32 v100, 0xbfb8aa3b, v110
	v_mul_f32_e32 v108, 0xbfb8aa3b, v111
	v_exp_f32_e32 v100, v100
	v_exp_f32_e32 v108, v108
	v_mul_f32_e32 v97, v109, v118
	v_mul_f32_e32 v97, v101, v97
	v_add_f32_e32 v100, 1.0, v100
	v_add_f32_e32 v101, 1.0, v108
	v_rcp_f32_e32 v100, v100
	v_rcp_f32_e32 v101, v101
	v_cvt_pk_bf16_f32 v96, v96, v97
	v_mul_f32_e32 v97, v110, v100
	v_mul_f32_e32 v100, v111, v101
	v_mul_f32_e32 v101, 0xbfb8aa3b, v104
	v_mul_f32_e32 v97, v102, v97
	v_exp_f32_e32 v101, v101
	v_mul_f32_e32 v102, 0xbfb8aa3b, v105
	v_exp_f32_e32 v102, v102
	v_mul_f32_e32 v100, v103, v100
	v_cvt_pk_bf16_f32 v97, v97, v100
	v_add_f32_e32 v100, 1.0, v101
	v_rcp_f32_e32 v100, v100
	v_add_f32_e32 v101, 1.0, v102
	v_mul_f32_e32 v102, 0xbfb8aa3b, v106
	v_rcp_f32_e32 v101, v101
	v_exp_f32_e32 v102, v102
	v_mul_f32_e32 v100, v104, v100
	v_mul_f32_e32 v98, v98, v100
	v_mul_f32_e32 v100, v105, v101
	v_add_f32_e32 v101, 1.0, v102
	v_rcp_f32_e32 v101, v101
	v_mul_f32_e32 v102, 0xbfb8aa3b, v107
	v_exp_f32_e32 v102, v102
	v_mul_f32_e32 v99, v99, v100
	v_cvt_pk_bf16_f32 v98, v98, v99
	v_mul_f32_e32 v99, v106, v101
	v_fmamk_f32 v101, v161, 0x3a800000, v154
	v_rsq_f32_e32 v101, v101
	v_add_f32_e32 v100, 1.0, v102
	v_rcp_f32_e32 v100, v100
	v_mul_f32_e32 v99, v116, v99
	v_mul_f32_e32 v100, v107, v100
	v_mul_f32_e32 v100, v117, v100
	v_cvt_pk_bf16_f32 v99, v99, v100
	flat_store_dwordx4 v[114:115], v[96:99]
	s_nop 1
	v_or_b32_e32 v97, 32, v144
	v_mov_b32_e32 v96, v101
	v_pk_mul_f32 v[92:93], v[96:97], v[92:93] op_sel_hi:[0,1]
	v_mad_i64_i32 v[98:99], s[8:9], v97, s59, v[146:147]
	v_pk_mul_f32 v[94:95], v[96:97], v[94:95] op_sel_hi:[0,1]
	v_pk_mul_f32 v[90:91], v[96:97], v[90:91] op_sel_hi:[0,1]
	v_pk_mul_f32 v[88:89], v[96:97], v[88:89] op_sel_hi:[0,1]
	v_pk_mul_f32 v[86:87], v[96:97], v[86:87] op_sel_hi:[0,1]
	v_pk_mul_f32 v[84:85], v[96:97], v[84:85] op_sel_hi:[0,1]
	v_mul_f32_e32 v97, 0xbfb8aa3b, v92
	v_exp_f32_e32 v97, v97
	v_mul_f32_e32 v100, 0xbfb8aa3b, v93
	v_exp_f32_e32 v102, v100
	v_lshl_add_u64 v[98:99], v[98:99], 0, v[148:149]
	v_pk_mul_f32 v[100:101], v[96:97], v[82:83] op_sel_hi:[0,1]
	v_add_f32_e32 v82, 1.0, v97
	v_rcp_f32_e32 v97, v82
	v_add_f32_e32 v82, 1.0, v102
	v_rcp_f32_e32 v102, v82
	v_pk_mul_f32 v[82:83], v[96:97], v[80:81] op_sel_hi:[0,1]
	v_mul_f32_e32 v80, v92, v97
	v_mul_f32_e32 v80, v84, v80
	v_mul_f32_e32 v84, 0xbfb8aa3b, v94
	v_mul_f32_e32 v92, 0xbfb8aa3b, v95
	v_exp_f32_e32 v84, v84
	v_exp_f32_e32 v92, v92
	v_mul_f32_e32 v81, v93, v102
	v_mul_f32_e32 v81, v85, v81
	v_add_f32_e32 v84, 1.0, v84
	v_add_f32_e32 v85, 1.0, v92
	v_rcp_f32_e32 v84, v84
	v_rcp_f32_e32 v85, v85
	v_cvt_pk_bf16_f32 v80, v80, v81
	v_mul_f32_e32 v81, v94, v84
	v_mul_f32_e32 v84, v95, v85
	v_mul_f32_e32 v85, 0xbfb8aa3b, v88
	v_mul_f32_e32 v81, v86, v81
	v_exp_f32_e32 v85, v85
	v_mul_f32_e32 v86, 0xbfb8aa3b, v89
	v_exp_f32_e32 v86, v86
	v_mul_f32_e32 v84, v87, v84
	v_cvt_pk_bf16_f32 v81, v81, v84
	v_add_f32_e32 v84, 1.0, v85
	v_rcp_f32_e32 v84, v84
	v_add_f32_e32 v85, 1.0, v86
	v_mul_f32_e32 v86, 0xbfb8aa3b, v90
	v_rcp_f32_e32 v85, v85
	v_exp_f32_e32 v86, v86
	v_mul_f32_e32 v84, v88, v84
	v_mul_f32_e32 v82, v82, v84
	v_mul_f32_e32 v84, v89, v85
	v_add_f32_e32 v85, 1.0, v86
	v_rcp_f32_e32 v85, v85
	v_mul_f32_e32 v86, 0xbfb8aa3b, v91
	v_exp_f32_e32 v86, v86
	v_mul_f32_e32 v83, v83, v84
	v_cvt_pk_bf16_f32 v82, v82, v83
	v_mul_f32_e32 v83, v90, v85
	v_fmamk_f32 v85, v160, 0x3a800000, v154
	v_rsq_f32_e32 v85, v85
	v_add_f32_e32 v84, 1.0, v86
	v_rcp_f32_e32 v84, v84
	v_mul_f32_e32 v83, v100, v83
	v_mul_f32_e32 v84, v91, v84
	v_mul_f32_e32 v84, v101, v84
	v_cvt_pk_bf16_f32 v83, v83, v84
	flat_store_dwordx4 v[98:99], v[80:83]
	s_nop 1
	v_or_b32_e32 v81, 48, v144
	v_mov_b32_e32 v80, v85
	v_pk_mul_f32 v[76:77], v[80:81], v[76:77] op_sel_hi:[0,1]
	v_mad_i64_i32 v[82:83], s[8:9], v81, s59, v[146:147]
	v_pk_mul_f32 v[78:79], v[80:81], v[78:79] op_sel_hi:[0,1]
	v_pk_mul_f32 v[74:75], v[80:81], v[74:75] op_sel_hi:[0,1]
	v_pk_mul_f32 v[72:73], v[80:81], v[72:73] op_sel_hi:[0,1]
	v_pk_mul_f32 v[70:71], v[80:81], v[70:71] op_sel_hi:[0,1]
	v_pk_mul_f32 v[68:69], v[80:81], v[68:69] op_sel_hi:[0,1]
	v_mul_f32_e32 v81, 0xbfb8aa3b, v76
	v_exp_f32_e32 v81, v81
	v_mul_f32_e32 v84, 0xbfb8aa3b, v77
	v_exp_f32_e32 v86, v84
	v_lshl_add_u64 v[82:83], v[82:83], 0, v[148:149]
	v_pk_mul_f32 v[84:85], v[80:81], v[66:67] op_sel_hi:[0,1]
	v_add_f32_e32 v66, 1.0, v81
	v_rcp_f32_e32 v81, v66
	v_add_f32_e32 v66, 1.0, v86
	v_rcp_f32_e32 v86, v66
	v_pk_mul_f32 v[66:67], v[80:81], v[64:65] op_sel_hi:[0,1]
	v_mul_f32_e32 v64, v76, v81
	v_mul_f32_e32 v64, v68, v64
	v_mul_f32_e32 v68, 0xbfb8aa3b, v78
	v_mul_f32_e32 v76, 0xbfb8aa3b, v79
	v_exp_f32_e32 v68, v68
	v_exp_f32_e32 v76, v76
	v_mul_f32_e32 v65, v77, v86
	v_mul_f32_e32 v65, v69, v65
	v_add_f32_e32 v68, 1.0, v68
	v_add_f32_e32 v69, 1.0, v76
	v_rcp_f32_e32 v68, v68
	v_rcp_f32_e32 v69, v69
	v_cvt_pk_bf16_f32 v64, v64, v65
	v_mul_f32_e32 v65, v78, v68
	v_mul_f32_e32 v68, v79, v69
	v_mul_f32_e32 v69, 0xbfb8aa3b, v72
	v_mul_f32_e32 v65, v70, v65
	v_exp_f32_e32 v69, v69
	v_mul_f32_e32 v70, 0xbfb8aa3b, v73
	v_exp_f32_e32 v70, v70
	v_mul_f32_e32 v68, v71, v68
	v_cvt_pk_bf16_f32 v65, v65, v68
	v_add_f32_e32 v68, 1.0, v69
	v_rcp_f32_e32 v68, v68
	v_add_f32_e32 v69, 1.0, v70
	v_mul_f32_e32 v70, 0xbfb8aa3b, v74
	v_rcp_f32_e32 v69, v69
	v_exp_f32_e32 v70, v70
	v_mul_f32_e32 v68, v72, v68
	v_mul_f32_e32 v66, v66, v68
	v_mul_f32_e32 v68, v73, v69
	v_add_f32_e32 v69, 1.0, v70
	v_rcp_f32_e32 v69, v69
	v_mul_f32_e32 v70, 0xbfb8aa3b, v75
	v_exp_f32_e32 v70, v70
	v_mul_f32_e32 v67, v67, v68
	v_cvt_pk_bf16_f32 v66, v66, v67
	v_mul_f32_e32 v67, v74, v69
	v_fmamk_f32 v69, v159, 0x3a800000, v154
	v_rsq_f32_e32 v69, v69
	v_add_f32_e32 v68, 1.0, v70
	v_rcp_f32_e32 v68, v68
	v_mul_f32_e32 v67, v84, v67
	v_mul_f32_e32 v68, v75, v68
	v_mul_f32_e32 v68, v85, v68
	v_cvt_pk_bf16_f32 v67, v67, v68
	flat_store_dwordx4 v[82:83], v[64:67]
	s_nop 1
	v_add_u32_e32 v65, 0x80, v144
	v_mov_b32_e32 v64, v69
	v_pk_mul_f32 v[60:61], v[64:65], v[60:61] op_sel_hi:[0,1]
	v_mad_i64_i32 v[66:67], s[8:9], v65, s59, v[146:147]
	v_pk_mul_f32 v[62:63], v[64:65], v[62:63] op_sel_hi:[0,1]
	v_pk_mul_f32 v[58:59], v[64:65], v[58:59] op_sel_hi:[0,1]
	v_pk_mul_f32 v[56:57], v[64:65], v[56:57] op_sel_hi:[0,1]
	v_pk_mul_f32 v[54:55], v[64:65], v[54:55] op_sel_hi:[0,1]
	v_pk_mul_f32 v[52:53], v[64:65], v[52:53] op_sel_hi:[0,1]
	v_mul_f32_e32 v65, 0xbfb8aa3b, v60
	v_exp_f32_e32 v65, v65
	v_mul_f32_e32 v68, 0xbfb8aa3b, v61
	v_exp_f32_e32 v70, v68
	v_lshl_add_u64 v[66:67], v[66:67], 0, v[148:149]
	v_pk_mul_f32 v[68:69], v[64:65], v[50:51] op_sel_hi:[0,1]
	v_add_f32_e32 v50, 1.0, v65
	v_rcp_f32_e32 v65, v50
	v_add_f32_e32 v50, 1.0, v70
	v_rcp_f32_e32 v70, v50
	v_pk_mul_f32 v[50:51], v[64:65], v[48:49] op_sel_hi:[0,1]
	v_mul_f32_e32 v48, v60, v65
	v_mul_f32_e32 v48, v52, v48
	v_mul_f32_e32 v52, 0xbfb8aa3b, v62
	v_mul_f32_e32 v60, 0xbfb8aa3b, v63
	v_exp_f32_e32 v52, v52
	v_exp_f32_e32 v60, v60
	v_mul_f32_e32 v49, v61, v70
	v_mul_f32_e32 v49, v53, v49
	v_add_f32_e32 v52, 1.0, v52
	v_add_f32_e32 v53, 1.0, v60
	v_rcp_f32_e32 v52, v52
	v_rcp_f32_e32 v53, v53
	v_cvt_pk_bf16_f32 v48, v48, v49
	v_mul_f32_e32 v49, v62, v52
	v_mul_f32_e32 v52, v63, v53
	v_mul_f32_e32 v53, 0xbfb8aa3b, v56
	v_mul_f32_e32 v49, v54, v49
	v_exp_f32_e32 v53, v53
	v_mul_f32_e32 v54, 0xbfb8aa3b, v57
	v_exp_f32_e32 v54, v54
	v_mul_f32_e32 v52, v55, v52
	v_cvt_pk_bf16_f32 v49, v49, v52
	v_add_f32_e32 v52, 1.0, v53
	v_rcp_f32_e32 v52, v52
	v_add_f32_e32 v53, 1.0, v54
	v_mul_f32_e32 v54, 0xbfb8aa3b, v58
	v_rcp_f32_e32 v53, v53
	v_exp_f32_e32 v54, v54
	v_mul_f32_e32 v52, v56, v52
	v_mul_f32_e32 v50, v50, v52
	v_mul_f32_e32 v52, v57, v53
	v_add_f32_e32 v53, 1.0, v54
	v_rcp_f32_e32 v53, v53
	v_mul_f32_e32 v54, 0xbfb8aa3b, v59
	v_exp_f32_e32 v54, v54
	v_mul_f32_e32 v51, v51, v52
	v_cvt_pk_bf16_f32 v50, v50, v51
	v_mul_f32_e32 v51, v58, v53
	v_fmamk_f32 v53, v158, 0x3a800000, v154
	v_rsq_f32_e32 v53, v53
	v_add_f32_e32 v52, 1.0, v54
	v_rcp_f32_e32 v52, v52
	v_mul_f32_e32 v51, v68, v51
	v_mul_f32_e32 v52, v59, v52
	v_mul_f32_e32 v52, v69, v52
	v_cvt_pk_bf16_f32 v51, v51, v52
	flat_store_dwordx4 v[66:67], v[48:51]
	s_nop 1
	v_add_u32_e32 v49, 0x90, v144
	v_mov_b32_e32 v48, v53
	v_pk_mul_f32 v[44:45], v[48:49], v[44:45] op_sel_hi:[0,1]
	v_mad_i64_i32 v[50:51], s[8:9], v49, s59, v[146:147]
	v_pk_mul_f32 v[46:47], v[48:49], v[46:47] op_sel_hi:[0,1]
	v_pk_mul_f32 v[42:43], v[48:49], v[42:43] op_sel_hi:[0,1]
	v_pk_mul_f32 v[40:41], v[48:49], v[40:41] op_sel_hi:[0,1]
	v_pk_mul_f32 v[38:39], v[48:49], v[38:39] op_sel_hi:[0,1]
	v_pk_mul_f32 v[36:37], v[48:49], v[36:37] op_sel_hi:[0,1]
	v_mul_f32_e32 v49, 0xbfb8aa3b, v44
	v_exp_f32_e32 v49, v49
	v_mul_f32_e32 v52, 0xbfb8aa3b, v45
	v_exp_f32_e32 v54, v52
	v_lshl_add_u64 v[50:51], v[50:51], 0, v[148:149]
	v_pk_mul_f32 v[52:53], v[48:49], v[34:35] op_sel_hi:[0,1]
	v_add_f32_e32 v34, 1.0, v49
	v_rcp_f32_e32 v49, v34
	v_add_f32_e32 v34, 1.0, v54
	v_rcp_f32_e32 v54, v34
	v_pk_mul_f32 v[34:35], v[48:49], v[32:33] op_sel_hi:[0,1]
	v_mul_f32_e32 v32, v44, v49
	v_mul_f32_e32 v32, v36, v32
	v_mul_f32_e32 v36, 0xbfb8aa3b, v46
	v_mul_f32_e32 v44, 0xbfb8aa3b, v47
	v_exp_f32_e32 v36, v36
	v_exp_f32_e32 v44, v44
	v_mul_f32_e32 v33, v45, v54
	v_mul_f32_e32 v33, v37, v33
	v_add_f32_e32 v36, 1.0, v36
	v_add_f32_e32 v37, 1.0, v44
	v_rcp_f32_e32 v36, v36
	v_rcp_f32_e32 v37, v37
	v_cvt_pk_bf16_f32 v32, v32, v33
	v_mul_f32_e32 v33, v46, v36
	v_mul_f32_e32 v36, v47, v37
	v_mul_f32_e32 v37, 0xbfb8aa3b, v40
	v_mul_f32_e32 v33, v38, v33
	v_exp_f32_e32 v37, v37
	v_mul_f32_e32 v38, 0xbfb8aa3b, v41
	v_exp_f32_e32 v38, v38
	v_mul_f32_e32 v36, v39, v36
	v_cvt_pk_bf16_f32 v33, v33, v36
	v_add_f32_e32 v36, 1.0, v37
	v_rcp_f32_e32 v36, v36
	v_add_f32_e32 v37, 1.0, v38
	v_mul_f32_e32 v38, 0xbfb8aa3b, v42
	v_rcp_f32_e32 v37, v37
	v_exp_f32_e32 v38, v38
	v_mul_f32_e32 v36, v40, v36
	v_mul_f32_e32 v34, v34, v36
	v_mul_f32_e32 v36, v41, v37
	v_add_f32_e32 v37, 1.0, v38
	v_rcp_f32_e32 v37, v37
	v_mul_f32_e32 v38, 0xbfb8aa3b, v43
	v_exp_f32_e32 v38, v38
	v_mul_f32_e32 v35, v35, v36
	v_cvt_pk_bf16_f32 v34, v34, v35
	v_mul_f32_e32 v35, v42, v37
	v_fmamk_f32 v37, v157, 0x3a800000, v154
	v_rsq_f32_e32 v37, v37
	v_add_f32_e32 v36, 1.0, v38
	v_rcp_f32_e32 v36, v36
	v_mul_f32_e32 v35, v52, v35
	v_mul_f32_e32 v36, v43, v36
	v_mul_f32_e32 v36, v53, v36
	v_cvt_pk_bf16_f32 v35, v35, v36
	flat_store_dwordx4 v[50:51], v[32:35]
	s_nop 1
	v_add_u32_e32 v33, 0xa0, v144
	v_mov_b32_e32 v32, v37
	v_pk_mul_f32 v[28:29], v[32:33], v[28:29] op_sel_hi:[0,1]
	v_mad_i64_i32 v[34:35], s[8:9], v33, s59, v[146:147]
	v_pk_mul_f32 v[30:31], v[32:33], v[30:31] op_sel_hi:[0,1]
	v_pk_mul_f32 v[26:27], v[32:33], v[26:27] op_sel_hi:[0,1]
	v_pk_mul_f32 v[24:25], v[32:33], v[24:25] op_sel_hi:[0,1]
	v_pk_mul_f32 v[22:23], v[32:33], v[22:23] op_sel_hi:[0,1]
	v_pk_mul_f32 v[20:21], v[32:33], v[20:21] op_sel_hi:[0,1]
	v_mul_f32_e32 v33, 0xbfb8aa3b, v28
	v_exp_f32_e32 v33, v33
	v_mul_f32_e32 v36, 0xbfb8aa3b, v29
	v_exp_f32_e32 v38, v36
	v_lshl_add_u64 v[34:35], v[34:35], 0, v[148:149]
	v_pk_mul_f32 v[36:37], v[32:33], v[18:19] op_sel_hi:[0,1]
	v_add_f32_e32 v18, 1.0, v33
	v_rcp_f32_e32 v33, v18
	v_add_f32_e32 v18, 1.0, v38
	v_rcp_f32_e32 v38, v18
	v_pk_mul_f32 v[18:19], v[32:33], v[16:17] op_sel_hi:[0,1]
	v_mul_f32_e32 v16, v28, v33
	v_mul_f32_e32 v16, v20, v16
	v_mul_f32_e32 v20, 0xbfb8aa3b, v30
	v_mul_f32_e32 v28, 0xbfb8aa3b, v31
	v_exp_f32_e32 v20, v20
	v_exp_f32_e32 v28, v28
	v_mul_f32_e32 v17, v29, v38
	v_mul_f32_e32 v17, v21, v17
	v_add_f32_e32 v20, 1.0, v20
	v_add_f32_e32 v21, 1.0, v28
	v_rcp_f32_e32 v20, v20
	v_rcp_f32_e32 v21, v21
	v_cvt_pk_bf16_f32 v16, v16, v17
	v_mul_f32_e32 v17, v30, v20
	v_mul_f32_e32 v20, v31, v21
	v_mul_f32_e32 v21, 0xbfb8aa3b, v24
	v_mul_f32_e32 v17, v22, v17
	v_exp_f32_e32 v21, v21
	v_mul_f32_e32 v22, 0xbfb8aa3b, v25
	v_exp_f32_e32 v22, v22
	v_mul_f32_e32 v20, v23, v20
	v_cvt_pk_bf16_f32 v17, v17, v20
	v_add_f32_e32 v20, 1.0, v21
	v_rcp_f32_e32 v20, v20
	v_add_f32_e32 v21, 1.0, v22
	v_mul_f32_e32 v22, 0xbfb8aa3b, v26
	v_rcp_f32_e32 v21, v21
	v_exp_f32_e32 v22, v22
	v_mul_f32_e32 v20, v24, v20
	v_mul_f32_e32 v18, v18, v20
	v_mul_f32_e32 v20, v25, v21
	v_add_f32_e32 v21, 1.0, v22
	v_rcp_f32_e32 v21, v21
	v_mul_f32_e32 v22, 0xbfb8aa3b, v27
	v_exp_f32_e32 v22, v22
	v_mul_f32_e32 v19, v19, v20
	v_cvt_pk_bf16_f32 v18, v18, v19
	v_mul_f32_e32 v19, v26, v21
	v_fmamk_f32 v21, v156, 0x3a800000, v154
	v_rsq_f32_e32 v21, v21
	v_add_f32_e32 v20, 1.0, v22
	v_rcp_f32_e32 v20, v20
	v_mul_f32_e32 v19, v36, v19
	v_mul_f32_e32 v20, v27, v20
	v_mul_f32_e32 v20, v37, v20
	v_cvt_pk_bf16_f32 v19, v19, v20
	flat_store_dwordx4 v[34:35], v[16:19]
	s_nop 1
	v_add_u32_e32 v17, 0xb0, v144
	v_mov_b32_e32 v16, v21
	v_pk_mul_f32 v[12:13], v[16:17], v[12:13] op_sel_hi:[0,1]
	v_mad_i64_i32 v[18:19], s[8:9], v17, s59, v[146:147]
	v_pk_mul_f32 v[14:15], v[16:17], v[14:15] op_sel_hi:[0,1]
	v_pk_mul_f32 v[10:11], v[16:17], v[10:11] op_sel_hi:[0,1]
	v_pk_mul_f32 v[8:9], v[16:17], v[8:9] op_sel_hi:[0,1]
	v_pk_mul_f32 v[6:7], v[16:17], v[6:7] op_sel_hi:[0,1]
	v_pk_mul_f32 v[4:5], v[16:17], v[4:5] op_sel_hi:[0,1]
	v_mul_f32_e32 v17, 0xbfb8aa3b, v12
	v_exp_f32_e32 v17, v17
	v_mul_f32_e32 v20, 0xbfb8aa3b, v13
	v_exp_f32_e32 v22, v20
	v_lshl_add_u64 v[18:19], v[18:19], 0, v[148:149]
	v_pk_mul_f32 v[20:21], v[16:17], v[2:3] op_sel_hi:[0,1]
	v_add_f32_e32 v2, 1.0, v17
	v_rcp_f32_e32 v17, v2
	v_add_f32_e32 v2, 1.0, v22
	v_rcp_f32_e32 v22, v2
	s_andn2_b64 vcc, exec, s[6:7]
	v_pk_mul_f32 v[2:3], v[16:17], v[0:1] op_sel_hi:[0,1]
	v_mul_f32_e32 v0, v12, v17
	v_mul_f32_e32 v0, v4, v0
	v_mul_f32_e32 v4, 0xbfb8aa3b, v14
	v_mul_f32_e32 v12, 0xbfb8aa3b, v15
	v_exp_f32_e32 v4, v4
	v_exp_f32_e32 v12, v12
	v_mul_f32_e32 v1, v13, v22
	v_mul_f32_e32 v1, v5, v1
	v_add_f32_e32 v4, 1.0, v4
	v_add_f32_e32 v5, 1.0, v12
	v_rcp_f32_e32 v4, v4
	v_rcp_f32_e32 v5, v5
	v_cvt_pk_bf16_f32 v0, v0, v1
	s_mov_b64 s[6:7], -1
	v_mul_f32_e32 v1, v14, v4
	v_mul_f32_e32 v4, v15, v5
	v_mul_f32_e32 v5, 0xbfb8aa3b, v8
	v_mul_f32_e32 v1, v6, v1
	v_exp_f32_e32 v5, v5
	v_mul_f32_e32 v6, 0xbfb8aa3b, v9
	v_exp_f32_e32 v6, v6
	v_mul_f32_e32 v4, v7, v4
	v_add_f32_e32 v5, 1.0, v5
	v_rcp_f32_e32 v5, v5
	v_add_f32_e32 v6, 1.0, v6
	v_rcp_f32_e32 v6, v6
	v_cvt_pk_bf16_f32 v1, v1, v4
	v_mul_f32_e32 v4, v8, v5
	v_mul_f32_e32 v5, 0xbfb8aa3b, v10
	v_mul_f32_e32 v2, v2, v4
	v_mul_f32_e32 v4, v9, v6
	v_exp_f32_e32 v5, v5
	v_mul_f32_e32 v6, 0xbfb8aa3b, v11
	v_exp_f32_e32 v6, v6
	v_mul_f32_e32 v3, v3, v4
	v_add_f32_e32 v4, 1.0, v5
	v_rcp_f32_e32 v4, v4
	v_add_f32_e32 v5, 1.0, v6
	v_rcp_f32_e32 v5, v5
	v_cvt_pk_bf16_f32 v2, v2, v3
	v_mul_f32_e32 v3, v10, v4
	v_mul_f32_e32 v3, v20, v3
	v_mul_f32_e32 v4, v11, v5
	v_mul_f32_e32 v4, v21, v4
	v_cvt_pk_bf16_f32 v3, v3, v4
	flat_store_dwordx4 v[18:19], v[0:3]
	s_cbranch_vccnz .LBB0_375
	s_andn2_b64 vcc, exec, s[10:11]
	s_cbranch_vccnz .LBB0_374
	s_barrier
	s_branch .LBB0_374
